# attention: software L2 prefetch of the next unit's Q rows and diagonal K rows by the map-1 waves at the start of the current unit's epilogue (next ticket passed through a spare LDS word)
# baseline (speedup 1.0000x reference)
; __device__ __forceinline__ void qk_fin(f32x16& n0, f32x16& n1, const char* Ks, const bf16x8* qr, int r32, int hi, int cbase,
;                                        const f32x16& q0, const f32x16& q1, float& l_reg, bf16x8& pa0, bf16x8& pa1, bf16x8& pa2, bf16x8& pa3) {
;   float ps = 0.f;
;   { const bf16x8 k0 = KFRAG(0, 0), k1 = KFRAG(0, 1); n0 = __builtin_amdgcn_mfma_f32_32x32x16_bf16(k0, qr[0], n0, 0, 0, 0); n1 = __builtin_amdgcn_mfma_f32_32x32x16_bf16(k1, qr[0], n1, 0, 0, 0); }
; #pragma unroll
;   for (int r = 0; r < 8; ++r) ps += q0[r];
;   PK4(q0, 0, pa0); asm volatile("" : "+v"(pa0), "+v"(ps)); SBAR();
;   { const bf16x8 k0 = KFRAG(1, 0), k1 = KFRAG(1, 1); n0 = __builtin_amdgcn_mfma_f32_32x32x16_bf16(k0, qr[1], n0, 0, 0, 0); n1 = __builtin_amdgcn_mfma_f32_32x32x16_bf16(k1, qr[1], n1, 0, 0, 0); }
; #pragma unroll
;   for (int r = 8; r < 16; ++r) ps += q0[r];
;   PK4(q0, 8, pa1); asm volatile("" : "+v"(pa1), "+v"(ps)); SBAR();
;   { const bf16x8 k0 = KFRAG(2, 0), k1 = KFRAG(2, 1); n0 = __builtin_amdgcn_mfma_f32_32x32x16_bf16(k0, qr[2], n0, 0, 0, 0); n1 = __builtin_amdgcn_mfma_f32_32x32x16_bf16(k1, qr[2], n1, 0, 0, 0); }
; #pragma unroll
;   for (int r = 0; r < 8; ++r) ps += q1[r];
;   PK4(q1, 0, pa2); asm volatile("" : "+v"(pa2), "+v"(ps)); SBAR();
;   { const bf16x8 k0 = KFRAG(3, 0), k1 = KFRAG(3, 1); n0 = __builtin_amdgcn_mfma_f32_32x32x16_bf16(k0, qr[3], n0, 0, 0, 0); n1 = __builtin_amdgcn_mfma_f32_32x32x16_bf16(k1, qr[3], n1, 0, 0, 0); }
; #pragma unroll
;   for (int r = 8; r < 16; ++r) ps += q1[r];
;   PK4(q1, 8, pa3);
;   { auto rr = __builtin_amdgcn_permlane32_swap(__float_as_uint(ps), __float_as_uint(ps), false, false); ps = __uint_as_float(rr[0]) + __uint_as_float(rr[1]); }
;   l_reg += ps; SBAR();
; }
; template <int D0> __device__ __forceinline__ void pv_one(f32x16& od, int vb, bf16x8 pa0, bf16x8 pa1, bf16x8 pa2, bf16x8 pa3) {
;   const s16x4 l0 = tr_read<v_rd_off(D0, 0, 0)>(vb), h0 = tr_read<v_rd_off(D0, 0, 1)>(vb), l1 = tr_read<v_rd_off(D0, 1, 0)>(vb), h1 = tr_read<v_rd_off(D0, 1, 1)>(vb);
;   const s16x4 l2 = tr_read<v_rd_off(D0, 2, 0)>(vb), h2 = tr_read<v_rd_off(D0, 2, 1)>(vb), l3 = tr_read<v_rd_off(D0, 3, 0)>(vb), h3 = tr_read<v_rd_off(D0, 3, 1)>(vb);
;   asm volatile("s_waitcnt lgkmcnt(0)" ::: "memory"); SBAR();
;     ...
;   od = __builtin_amdgcn_mfma_f32_32x32x16_bf16(pa0, PK(l0, h0), od, 0, 0, 0);
.LBB0_340:
	v_and_b32_e32 v144, 0x3fffffc0, v229
	v_lshl_add_u32 v144, v144, 2, s10
	v_add3_u32 v145, 0, v236, v232
	ds_read_b128 v[146:149], v145 offset:49152
	ds_read_b128 v[150:153], v145 offset:57344
	s_waitcnt lgkmcnt(1)
	v_mfma_f32_32x32x16_bf16 v[112:127], v[146:149], v[132:135], v[112:127]
	s_waitcnt lgkmcnt(0)
	v_mfma_f32_32x32x16_bf16 v[96:111], v[150:153], v[132:135], v[96:111]
	v_add_f32_e32 v132, 0, v80
	v_add_f32_e32 v132, v81, v132
	v_add_f32_e32 v132, v82, v132
	v_add_f32_e32 v132, v83, v132
	v_add_f32_e32 v132, v84, v132
	v_add_f32_e32 v132, v85, v132
	v_add_f32_e32 v132, v86, v132
	v_cvt_pk_bf16_f32 v80, v80, v81
	v_cvt_pk_bf16_f32 v81, v82, v83
	v_cvt_pk_bf16_f32 v82, v84, v85
	v_cvt_pk_bf16_f32 v83, v86, v87
	v_add_f32_e32 v132, v87, v132
	v_permlane32_swap_b32_e32 v80, v82
	v_permlane32_swap_b32_e32 v81, v83
	v_add3_u32 v133, 0, v235, v232
	ds_read_b128 v[84:87], v133 offset:49152
	v_add_f32_e32 v145, v88, v132
	ds_read_b128 v[132:135], v133 offset:57344
	v_add_f32_e32 v145, v89, v145
	v_add_f32_e32 v145, v90, v145
	s_waitcnt lgkmcnt(1)
	v_mfma_f32_32x32x16_bf16 v[112:127], v[84:87], v[128:131], v[112:127]
	v_add_f32_e32 v84, v91, v145
	v_add_f32_e32 v84, v92, v84
	v_add_f32_e32 v84, v93, v84
	v_add_f32_e32 v84, v94, v84
	v_add_f32_e32 v145, v95, v84
	v_cvt_pk_bf16_f32 v84, v88, v89
	v_cvt_pk_bf16_f32 v85, v90, v91
	v_cvt_pk_bf16_f32 v86, v92, v93
	v_cvt_pk_bf16_f32 v87, v94, v95
	s_waitcnt lgkmcnt(0)
	v_mfma_f32_32x32x16_bf16 v[96:111], v[132:135], v[128:131], v[96:111]
	v_permlane32_swap_b32_e32 v84, v86
	v_permlane32_swap_b32_e32 v85, v87
	v_add3_u32 v92, 0, v234, v232
	ds_read_b128 v[88:91], v92 offset:49152
	ds_read_b128 v[92:95], v92 offset:57344
	v_add_f32_e32 v128, v64, v145
	v_add_f32_e32 v128, v65, v128
	v_add_f32_e32 v128, v66, v128
	v_cvt_pk_bf16_f32 v64, v64, v65
	v_cvt_pk_bf16_f32 v65, v66, v67
	v_cvt_pk_bf16_f32 v66, v68, v69
	s_waitcnt lgkmcnt(1)
	v_mfma_f32_32x32x16_bf16 v[112:127], v[88:91], v[140:143], v[112:127]
	v_add_f32_e32 v88, v67, v128
	v_add_f32_e32 v88, v68, v88
	v_add_f32_e32 v88, v69, v88
	v_add_f32_e32 v88, v70, v88
	v_cvt_pk_bf16_f32 v67, v70, v71
	v_add_f32_e32 v128, v71, v88
	v_permlane32_swap_b32_e32 v64, v66
	v_permlane32_swap_b32_e32 v65, v67
	s_waitcnt lgkmcnt(0)
	v_mfma_f32_32x32x16_bf16 v[96:111], v[92:95], v[140:143], v[96:111]
	v_add3_u32 v88, 0, v233, v232
	ds_read_b128 v[68:71], v88 offset:49152
	ds_read_b128 v[88:91], v88 offset:57344
	s_waitcnt lgkmcnt(1)
	v_mfma_f32_32x32x16_bf16 v[112:127], v[68:71], v[136:139], v[112:127]
	v_add_f32_e32 v68, v72, v128
	v_add_f32_e32 v68, v73, v68
	v_add_f32_e32 v68, v74, v68
	v_add_f32_e32 v68, v75, v68
	v_add_f32_e32 v68, v76, v68
	v_add_f32_e32 v68, v77, v68
	v_add_f32_e32 v68, v78, v68
	s_waitcnt lgkmcnt(0)
	v_mfma_f32_32x32x16_bf16 v[96:111], v[88:91], v[136:139], v[96:111]
	v_add_f32_e32 v88, v79, v68
	v_cvt_pk_bf16_f32 v68, v72, v73
	v_cvt_pk_bf16_f32 v69, v74, v75
	v_cvt_pk_bf16_f32 v70, v76, v77
	v_mov_b32_e32 v72, v88
	v_cvt_pk_bf16_f32 v71, v78, v79
	v_permlane32_swap_b32_e32 v68, v70
	s_nop 0
	v_permlane32_swap_b32_e32 v88, v72
	v_permlane32_swap_b32_e32 v69, v71
	ds_read_b64_tr_b16 v[74:75], v230 offset:0
	ds_read_b64_tr_b16 v[76:77], v230 offset:0x800
	ds_read_b64_tr_b16 v[90:91], v230 offset:0x1000
	ds_read_b64_tr_b16 v[92:93], v230 offset:0x1800
	ds_read_b64_tr_b16 v[128:129], v230 offset:0x2000
	ds_read_b64_tr_b16 v[130:131], v230 offset:0x2800
	ds_read_b64_tr_b16 v[132:133], v230 offset:0x3000
	ds_read_b64_tr_b16 v[134:135], v230 offset:0x3800
	s_waitcnt lgkmcnt(0)
	s_nop 0
	v_mfma_f32_32x32x16_bf16 v[48:63], v[80:83], v[74:77], v[48:63]
	v_exp_f32_e32 v112, v112
	v_exp_f32_e32 v113, v113
	v_exp_f32_e32 v114, v114
	v_exp_f32_e32 v115, v115
	v_exp_f32_e32 v116, v116
	v_exp_f32_e32 v117, v117
	v_exp_f32_e32 v118, v118
	v_mfma_f32_32x32x16_bf16 v[48:63], v[84:87], v[90:93], v[48:63]
	v_exp_f32_e32 v119, v119
	v_mfma_f32_32x32x16_bf16 v[48:63], v[64:67], v[128:131], v[48:63]
	v_mfma_f32_32x32x16_bf16 v[48:63], v[68:71], v[132:135], v[48:63]
	ds_read_b64_tr_b16 v[74:75], v230 offset:0x200
	ds_read_b64_tr_b16 v[76:77], v230 offset:0xa00
	ds_read_b64_tr_b16 v[90:91], v230 offset:0x1200
	ds_read_b64_tr_b16 v[92:93], v230 offset:0x1a00
	ds_read_b64_tr_b16 v[128:129], v230 offset:0x2200
	ds_read_b64_tr_b16 v[130:131], v230 offset:0x2a00
	ds_read_b64_tr_b16 v[132:133], v230 offset:0x3200
	ds_read_b64_tr_b16 v[134:135], v230 offset:0x3a00
	s_waitcnt lgkmcnt(0)
	s_nop 0
	v_mfma_f32_32x32x16_bf16 v[32:47], v[80:83], v[74:77], v[32:47]
	v_exp_f32_e32 v120, v120
	v_exp_f32_e32 v121, v121
	v_exp_f32_e32 v122, v122
	v_exp_f32_e32 v123, v123
	v_exp_f32_e32 v124, v124
	v_exp_f32_e32 v125, v125
	v_exp_f32_e32 v126, v126
	v_mfma_f32_32x32x16_bf16 v[32:47], v[84:87], v[90:93], v[32:47]
	v_exp_f32_e32 v127, v127
	v_mfma_f32_32x32x16_bf16 v[32:47], v[64:67], v[128:131], v[32:47]
	v_mfma_f32_32x32x16_bf16 v[32:47], v[68:71], v[132:135], v[32:47]
	ds_read_b64_tr_b16 v[74:75], v230 offset:0x400
	ds_read_b64_tr_b16 v[76:77], v230 offset:0xc00
	ds_read_b64_tr_b16 v[90:91], v230 offset:0x1400
	ds_read_b64_tr_b16 v[92:93], v230 offset:0x1c00
	ds_read_b64_tr_b16 v[128:129], v230 offset:0x2400
	ds_read_b64_tr_b16 v[130:131], v230 offset:0x2c00
	ds_read_b64_tr_b16 v[132:133], v230 offset:0x3400
	ds_read_b64_tr_b16 v[134:135], v230 offset:0x3c00
	s_waitcnt lgkmcnt(0)
; __device__ __forceinline__ void fin_only(const f32x16& q0, const f32x16& q1, float& l_reg, bf16x8& pa0, bf16x8& pa1, bf16x8& pa2, bf16x8& pa3) {
;   float ps = 0.f;
; #pragma unroll
;   for (int r = 0; r < 16; ++r) ps += q0[r];
; #pragma unroll
;   for (int r = 0; r < 16; ++r) ps += q1[r];
;   { auto rr = __builtin_amdgcn_permlane32_swap(__float_as_uint(ps), __float_as_uint(ps), false, false); ps = __uint_as_float(rr[0]) + __uint_as_float(rr[1]); }
;   l_reg += ps; PK4(q0, 0, pa0); PK4(q0, 8, pa1); PK4(q1, 0, pa2); PK4(q1, 8, pa3);
; }
; __device__ __forceinline__ int v_st(int k, int c) { const int kk = (k & ~0xC) | ((k & 4) << 1) | ((k & 8) >> 1); return ((kk >> 3) * 4 + (c >> 5)) * 512 + ((kk & 7) * 32 + (c & 31)) * 2; }
; __device__ __forceinline__ int v_rd_base(int lane) { return ((lane & 3) << 3) | (((lane >> 2) & 3) << 6) | (((lane >> 4) & 1) << 5) | (((lane >> 5) & 1) << 8); }
; template <int OFF> __device__ __forceinline__ s16x4 tr_read(int vb) {
;   s16x4 r; asm volatile("ds_read_b64_tr_b16 %0, %1 offset:%2" : "=&v"(r) : "v"(vb), "i"(OFF) : "memory"); return r;
; }
; template <int D0> __device__ __forceinline__ void pv_one(f32x16& od, int vb, bf16x8 pa0, bf16x8 pa1, bf16x8 pa2, bf16x8 pa3) {
;   const s16x4 l0 = tr_read<v_rd_off(D0, 0, 0)>(vb), h0 = tr_read<v_rd_off(D0, 0, 1)>(vb), l1 = tr_read<v_rd_off(D0, 1, 0)>(vb), h1 = tr_read<v_rd_off(D0, 1, 1)>(vb);
;   const s16x4 l2 = tr_read<v_rd_off(D0, 2, 0)>(vb), h2 = tr_read<v_rd_off(D0, 2, 1)>(vb), l3 = tr_read<v_rd_off(D0, 3, 0)>(vb), h3 = tr_read<v_rd_off(D0, 3, 1)>(vb);
;   asm volatile("s_waitcnt lgkmcnt(0)" ::: "memory"); SBAR();
;     ...
;   od = __builtin_amdgcn_mfma_f32_32x32x16_bf16(pa0, PK(l0, h0), od, 0, 0, 0);
;   od = __builtin_amdgcn_mfma_f32_32x32x16_bf16(pa1, PK(l1, h1), od, 0, 0, 0);
;   od = __builtin_amdgcn_mfma_f32_32x32x16_bf16(pa2, PK(l2, h2), od, 0, 0, 0);
;   od = __builtin_amdgcn_mfma_f32_32x32x16_bf16(pa3, PK(l3, h3), od, 0, 0, 0);
;     ...
; }
; __device__ __forceinline__ void pv_exp(f32x16* o, int vb, bf16x8 pa0, bf16x8 pa1, bf16x8 pa2, bf16x8 pa3, f32x16& n0, f32x16& n1) {
;   pv_one<0>(o[0], vb, pa0, pa1, pa2, pa3);
; #pragma unroll
;   for (int r = 0; r < 8; ++r) n0[r] = __builtin_amdgcn_exp2f(n0[r]);
;   asm volatile("" : "+v"(n0)); SBAR(); pv_one<1>(o[1], vb, pa0, pa1, pa2, pa3);
; #pragma unroll
;   for (int r = 8; r < 16; ++r) n0[r] = __builtin_amdgcn_exp2f(n0[r]);
	s_nop 0
	v_mfma_f32_32x32x16_bf16 v[16:31], v[80:83], v[74:77], v[16:31]
	v_exp_f32_e32 v96, v96
	v_exp_f32_e32 v97, v97
	v_exp_f32_e32 v98, v98
	v_exp_f32_e32 v99, v99
	v_exp_f32_e32 v100, v100
	v_exp_f32_e32 v101, v101
	v_exp_f32_e32 v102, v102
	v_mfma_f32_32x32x16_bf16 v[16:31], v[84:87], v[90:93], v[16:31]
	v_exp_f32_e32 v103, v103
	v_mfma_f32_32x32x16_bf16 v[16:31], v[64:67], v[128:131], v[16:31]
	v_mfma_f32_32x32x16_bf16 v[16:31], v[68:71], v[132:135], v[16:31]
	ds_read_b64_tr_b16 v[74:75], v230 offset:0x600
	ds_read_b64_tr_b16 v[76:77], v230 offset:0xe00
	ds_read_b64_tr_b16 v[90:91], v230 offset:0x1600
	ds_read_b64_tr_b16 v[92:93], v230 offset:0x1e00
	ds_read_b64_tr_b16 v[128:129], v230 offset:0x2600
	ds_read_b64_tr_b16 v[130:131], v230 offset:0x2e00
	ds_read_b64_tr_b16 v[132:133], v230 offset:0x3600
	ds_read_b64_tr_b16 v[134:135], v230 offset:0x3e00
	s_waitcnt lgkmcnt(0)
	s_nop 0
	v_mfma_f32_32x32x16_bf16 v[0:15], v[80:83], v[74:77], v[0:15]
	v_exp_f32_e32 v104, v104
	v_exp_f32_e32 v105, v105
	v_exp_f32_e32 v106, v106
	v_exp_f32_e32 v107, v107
	v_exp_f32_e32 v108, v108
	v_exp_f32_e32 v109, v109
	v_exp_f32_e32 v110, v110
	v_mfma_f32_32x32x16_bf16 v[0:15], v[84:87], v[90:93], v[0:15]
	v_exp_f32_e32 v111, v111
	v_mfma_f32_32x32x16_bf16 v[0:15], v[64:67], v[128:131], v[0:15]
	v_mfma_f32_32x32x16_bf16 v[0:15], v[68:71], v[132:135], v[0:15]
	v_add_f32_e32 v64, 0, v112
	v_add_f32_e32 v64, v113, v64
	v_add_f32_e32 v64, v114, v64
	v_add_f32_e32 v64, v115, v64
	v_add_f32_e32 v64, v116, v64
	v_add_f32_e32 v64, v117, v64
	v_add_f32_e32 v64, v118, v64
	v_add_f32_e32 v64, v119, v64
	v_add_f32_e32 v64, v120, v64
	v_add_f32_e32 v64, v121, v64
	v_add_f32_e32 v64, v122, v64
	v_add_f32_e32 v64, v123, v64
	v_add_f32_e32 v64, v124, v64
	v_add_f32_e32 v64, v125, v64
	v_add_f32_e32 v64, v126, v64
	v_add_f32_e32 v64, v127, v64
	v_add_f32_e32 v64, v64, v96
	v_add_f32_e32 v64, v97, v64
	v_add_f32_e32 v64, v98, v64
	v_add_f32_e32 v64, v99, v64
	v_add_f32_e32 v64, v100, v64
	v_add_f32_e32 v64, v101, v64
	v_add_f32_e32 v64, v102, v64
	v_add_f32_e32 v64, v103, v64
	v_add_f32_e32 v64, v104, v64
	v_add_f32_e32 v64, v105, v64
	v_add_f32_e32 v64, v106, v64
	v_add_f32_e32 v64, v107, v64
	v_add_f32_e32 v64, v108, v64
	v_add_f32_e32 v64, v109, v64
	v_add_f32_e32 v64, v110, v64
	v_add_f32_e32 v89, v111, v64
	v_mov_b32_e32 v73, v89
	v_cvt_pk_bf16_f32 v64, v112, v113
	v_cvt_pk_bf16_f32 v65, v114, v115
	v_cvt_pk_bf16_f32 v66, v116, v117
	v_cvt_pk_bf16_f32 v67, v118, v119
	v_cvt_pk_bf16_f32 v68, v120, v121
	v_cvt_pk_bf16_f32 v69, v122, v123
	v_cvt_pk_bf16_f32 v70, v124, v125
	v_cvt_pk_bf16_f32 v71, v126, v127
	v_cvt_pk_bf16_f32 v74, v96, v97
	v_cvt_pk_bf16_f32 v75, v98, v99
	v_cvt_pk_bf16_f32 v76, v100, v101
	v_cvt_pk_bf16_f32 v77, v102, v103
	s_nop 1
	v_permlane32_swap_b32_e32 v89, v73
	v_permlane32_swap_b32_e32 v68, v70
	v_permlane32_swap_b32_e32 v74, v76
	v_permlane32_swap_b32_e32 v75, v77
	v_cvt_pk_bf16_f32 v78, v104, v105
	v_cvt_pk_bf16_f32 v79, v106, v107
	v_cvt_pk_bf16_f32 v80, v108, v109
	v_cvt_pk_bf16_f32 v81, v110, v111
	v_permlane32_swap_b32_e32 v64, v66
	v_permlane32_swap_b32_e32 v65, v67
	v_permlane32_swap_b32_e32 v69, v71
	v_permlane32_swap_b32_e32 v78, v80
	v_permlane32_swap_b32_e32 v79, v81
	s_cmp_lg_u32 0, -1
	s_cselect_b32 s0, 0, 0
	s_addk_i32 s0, 0x4000
	v_add_u32_e32 v86, s0, v176
	ds_read_b64_tr_b16 v[82:83], v86 offset:0
	ds_read_b64_tr_b16 v[84:85], v86 offset:0x800
	ds_read_b64_tr_b16 v[90:91], v86 offset:0x1000
	ds_read_b64_tr_b16 v[92:93], v86 offset:0x1800
	ds_read_b64_tr_b16 v[94:95], v86 offset:0x2000
	ds_read_b64_tr_b16 v[96:97], v86 offset:0x2800
	ds_read_b64_tr_b16 v[98:99], v86 offset:0x3000
	ds_read_b64_tr_b16 v[100:101], v86 offset:0x3800
	s_waitcnt lgkmcnt(0)
	s_nop 0
	v_mfma_f32_32x32x16_bf16 v[48:63], v[64:67], v[82:85], v[48:63]
	ds_read_b64_tr_b16 v[82:83], v86 offset:0x200
	ds_read_b64_tr_b16 v[84:85], v86 offset:0xa00
	v_mfma_f32_32x32x16_bf16 v[48:63], v[68:71], v[90:93], v[48:63]
	ds_read_b64_tr_b16 v[90:91], v86 offset:0x1200
	ds_read_b64_tr_b16 v[92:93], v86 offset:0x1a00
	v_mfma_f32_32x32x16_bf16 v[48:63], v[74:77], v[94:97], v[48:63]
	ds_read_b64_tr_b16 v[94:95], v86 offset:0x2200
	ds_read_b64_tr_b16 v[96:97], v86 offset:0x2a00
	v_mfma_f32_32x32x16_bf16 v[48:63], v[78:81], v[98:101], v[48:63]
	ds_read_b64_tr_b16 v[98:99], v86 offset:0x3200
	ds_read_b64_tr_b16 v[100:101], v86 offset:0x3a00
	s_waitcnt lgkmcnt(0)
	v_mfma_f32_32x32x16_bf16 v[32:47], v[64:67], v[82:85], v[32:47]
	ds_read_b64_tr_b16 v[82:83], v86 offset:0x400
	ds_read_b64_tr_b16 v[84:85], v86 offset:0xc00
	v_mfma_f32_32x32x16_bf16 v[32:47], v[68:71], v[90:93], v[32:47]
	ds_read_b64_tr_b16 v[90:91], v86 offset:0x1400
	ds_read_b64_tr_b16 v[92:93], v86 offset:0x1c00
	v_mfma_f32_32x32x16_bf16 v[32:47], v[74:77], v[94:97], v[32:47]
	ds_read_b64_tr_b16 v[94:95], v86 offset:0x2400
	ds_read_b64_tr_b16 v[96:97], v86 offset:0x2c00
	v_mfma_f32_32x32x16_bf16 v[32:47], v[78:81], v[98:101], v[32:47]
	ds_read_b64_tr_b16 v[98:99], v86 offset:0x3400
	ds_read_b64_tr_b16 v[100:101], v86 offset:0x3c00
	s_waitcnt lgkmcnt(0)
	v_mfma_f32_32x32x16_bf16 v[16:31], v[64:67], v[82:85], v[16:31]
	ds_read_b64_tr_b16 v[82:83], v86 offset:0x600
	ds_read_b64_tr_b16 v[84:85], v86 offset:0xe00
	v_mfma_f32_32x32x16_bf16 v[16:31], v[68:71], v[90:93], v[16:31]
	ds_read_b64_tr_b16 v[90:91], v86 offset:0x1600
	ds_read_b64_tr_b16 v[92:93], v86 offset:0x1e00
	v_mfma_f32_32x32x16_bf16 v[16:31], v[74:77], v[94:97], v[16:31]
	ds_read_b64_tr_b16 v[94:95], v86 offset:0x2600
	ds_read_b64_tr_b16 v[96:97], v86 offset:0x2e00
	v_mfma_f32_32x32x16_bf16 v[16:31], v[78:81], v[98:101], v[16:31]
	ds_read_b64_tr_b16 v[98:99], v86 offset:0x3600
	ds_read_b64_tr_b16 v[100:101], v86 offset:0x3e00
	s_waitcnt lgkmcnt(0)
; __device__ __forceinline__ int crow(int r, int hi) { return (r & 3) + 8 * (r >> 2) + 4 * hi; }
; __device__ __forceinline__ void attn_unit(const bf16* __restrict__ P, bf16* __restrict__ MIXIN, const float* __restrict__ gn, int seq0, int h, int q0, int nt, float kmax0, float kmax1, float slope, float lam, char* lds) {
;     ...
;   int tide_ = threadIdx.x; asm volatile("" : "+v"(tide_)); const int lanee = tide_ & 63, r32e = lanee & 31, hie = lanee >> 5, wide = tide_ >> 6, wqe = wide & 3, mpe = wide >> 2;
;   if (hie == 0) li_l[r32e] = l_reg; asm volatile("s_waitcnt lgkmcnt(0)" ::: "memory");
;   float rli[16];
; #pragma unroll
;   for (int r = 0; r < 16; ++r) rli[r] = __builtin_amdgcn_rcpf(li_l[crow(r, hie)]);
;   asm volatile("s_waitcnt vmcnt(0)" ::: "memory");
;   __syncthreads();
;   float* X = (float*)lds;
;   if (mpe == 1) {
; __global__ void __launch_bounds__(NWAVES * 64, 2) hymba_fwd(Args args) {
;     ...
;             int seq0, h, q0, nt, sq;
;             if (u < 512) { h = 3 - (u >> 7); q0 = (u & 127) * 128; seq0 = NPROMPT; nt = SS / 64; sq = 16; }
;             else { const int v = u - 512; h = 3 - (v >> 8); sq = (v >> 4) & 15; q0 = (v & 15) * 128; seq0 = sq * SP; nt = SP / 64; }
	v_mfma_f32_32x32x16_bf16 v[0:15], v[64:67], v[82:85], v[0:15]
	v_mfma_f32_32x32x16_bf16 v[0:15], v[68:71], v[90:93], v[0:15]
	v_mfma_f32_32x32x16_bf16 v[0:15], v[74:77], v[94:97], v[0:15]
	v_mov_b32_e32 v77, v210
	s_nop 0
	v_and_b32_e32 v68, 63, v77
	v_and_b32_e32 v76, 31, v77
	v_cmp_gt_u32_e32 vcc, 32, v68
	v_mfma_f32_32x32x16_bf16 v[0:15], v[78:81], v[98:101], v[0:15]
	s_and_saveexec_b64 s[0:1], vcc
	v_pk_add_f32 v[64:65], v[88:89], v[72:73]
	v_lshl_add_u32 v66, v76, 2, v144
	v_add_f32_e32 v64, v231, v64
	v_add_f32_e32 v64, v64, v65
	ds_write_b32 v66, v64
	s_or_b64 exec, exec, s[0:1]
	v_lshrrev_b32_e32 v78, 5, v68
	s_waitcnt lgkmcnt(0)
	v_lshl_add_u32 v69, v78, 4, v144
	ds_read_b128 v[64:67], v69
	ds_read_b128 v[70:73], v69 offset:32
	v_lshlrev_b32_e32 v90, 8, v77
	s_waitcnt lgkmcnt(1)
	v_rcp_f32_e32 v94, v64
	v_rcp_f32_e32 v96, v65
	v_rcp_f32_e32 v92, v66
	v_rcp_f32_e32 v93, v67
	s_waitcnt lgkmcnt(0)
	v_rcp_f32_e32 v89, v70
	ds_read_b128 v[64:67], v69 offset:64
	v_rcp_f32_e32 v91, v71
	v_rcp_f32_e32 v80, v72
	v_rcp_f32_e32 v81, v73
	ds_read_b128 v[70:73], v69 offset:96
	s_waitcnt lgkmcnt(1)
	v_rcp_f32_e32 v87, v64
	v_rcp_f32_e32 v88, v65
	v_rcp_f32_e32 v85, v66
	v_rcp_f32_e32 v86, v67
	s_waitcnt lgkmcnt(0)
	v_rcp_f32_e32 v83, v70
	v_rcp_f32_e32 v84, v71
	v_rcp_f32_e32 v82, v72
	v_rcp_f32_e32 v79, v73
	s_waitcnt vmcnt(0)
	s_and_saveexec_b64 s[98:99], s[22:23]
	s_cbranch_execz .Lattn_pf0
	ds_write_b32 v219, v175 offset:16
	s_waitcnt lgkmcnt(0)
.Lattn_pf0:
	s_or_b64 exec, exec, s[98:99]
	v_and_b32_e32 v64, 0xffffff00, v77
	v_cmp_eq_u32_e32 vcc, s28, v64
	v_and_b32_e32 v69, 0xc000, v90
	s_barrier
	s_and_saveexec_b64 s[0:1], vcc
	s_cbranch_execz .LBB0_344
	ds_read_b32 v186, v219 offset:16
	v_and_b32_e32 v187, 31, v210
	v_lshrrev_b32_e32 v188, 1, v210
	v_and_b32_e32 v188, 0x60, v188
	v_or_b32_e32 v187, v187, v188
	v_mul_u32_u24_e32 v187, 0x1a00, v187
	v_and_b32_e32 v188, 32, v210
	v_lshl_add_u32 v187, v188, 2, v187
	s_waitcnt lgkmcnt(0)
	v_readfirstlane_b32 s100, v186
	s_nop 0
	s_cmpk_gt_u32 s100, 0x5ff
	s_cbranch_scc1 .Lattn_pf1
	s_cmpk_gt_u32 s100, 0x1ff
	s_cbranch_scc0 .Lattn_pf_s
	s_bfe_u32 s98, s100, 0x40004
	s_lshl_b32 s98, s98, 11
	s_and_b32 s99, s100, 15
	s_lshl_b32 s99, s99, 7
	s_add_i32 s101, s100, 0xfffffe00
	s_lshr_b32 s101, s101, 8
	s_branch .Lattn_pf_c
.Lattn_pf_s:
	s_mov_b32 s98, 0x8000
	s_and_b32 s99, s100, 0x7f
	s_lshl_b32 s99, s99, 7
	s_lshr_b32 s101, s100, 7
.Lattn_pf_c:
	s_add_i32 s98, s98, s99
	s_mul_i32 s98, s98, 0x1a00
	s_sub_i32 s101, 3, s101
	s_lshl_b32 s101, s101, 8
	s_add_i32 s98, s98, s101
	v_add_u32_e32 v188, s98, v187
	v_mov_b32_e32 v189, 0
	v_lshl_add_u64 v[188:189], s[44:45], 0, v[188:189]
	global_load_dword v174, v[188:189], off
	global_load_dword v174, v[188:189], off offset:1024
; __device__ __forceinline__ void attn_unit(const bf16* __restrict__ P, bf16* __restrict__ MIXIN, const float* __restrict__ gn, int seq0, int h, int q0, int nt, float kmax0, float kmax1, float slope, float lam, char* lds) {
;     ...
;   float* X = (float*)lds;
;   if (mpe == 1) {
; #pragma unroll
;     for (int d0 = 0; d0 < 4; ++d0)
; #pragma unroll
;       for (int r = 0; r < 16; ++r) X[(wqe * 64 + d0 * 16 + r) * 64 + lanee] = o[d0][r] * rli[r] * lam;
;   }
.Lattn_pf1:
	v_lshlrev_b32_e32 v64, 2, v68
	v_mul_f32_e32 v65, v48, v94
	v_mul_f32_e32 v66, v49, v96
	v_mul_f32_e32 v65, v183, v65
	v_add3_u32 v64, 0, v64, v69
	v_mul_f32_e32 v66, v183, v66
	ds_write2st64_b32 v64, v65, v66 offset1:1
	v_mul_f32_e32 v65, v50, v92
	v_mul_f32_e32 v66, v51, v93
	v_mul_f32_e32 v65, v183, v65
	v_mul_f32_e32 v66, v183, v66
	ds_write2st64_b32 v64, v65, v66 offset0:2 offset1:3
	v_mul_f32_e32 v65, v52, v89
	v_mul_f32_e32 v66, v53, v91
	v_mul_f32_e32 v65, v183, v65
	v_mul_f32_e32 v66, v183, v66
	ds_write2st64_b32 v64, v65, v66 offset0:4 offset1:5
	v_mul_f32_e32 v65, v54, v80
	v_mul_f32_e32 v66, v55, v81
	v_mul_f32_e32 v65, v183, v65
	v_mul_f32_e32 v66, v183, v66
	ds_write2st64_b32 v64, v65, v66 offset0:6 offset1:7
	v_mul_f32_e32 v65, v56, v87
	v_mul_f32_e32 v66, v57, v88
	v_mul_f32_e32 v65, v183, v65
	v_mul_f32_e32 v66, v183, v66
	ds_write2st64_b32 v64, v65, v66 offset0:8 offset1:9
	v_mul_f32_e32 v65, v58, v85
	v_mul_f32_e32 v66, v59, v86
	v_mul_f32_e32 v65, v183, v65
	v_mul_f32_e32 v66, v183, v66
	ds_write2st64_b32 v64, v65, v66 offset0:10 offset1:11
	v_mul_f32_e32 v65, v60, v83
	v_mul_f32_e32 v66, v61, v84
	v_mul_f32_e32 v65, v183, v65
	v_mul_f32_e32 v66, v183, v66
	ds_write2st64_b32 v64, v65, v66 offset0:12 offset1:13
	v_mul_f32_e32 v65, v62, v82
	v_mul_f32_e32 v66, v63, v79
	v_mul_f32_e32 v65, v183, v65
	v_mul_f32_e32 v66, v183, v66
	ds_write2st64_b32 v64, v65, v66 offset0:14 offset1:15
	v_mul_f32_e32 v65, v32, v94
	v_mul_f32_e32 v66, v33, v96
	v_mul_f32_e32 v65, v183, v65
	v_mul_f32_e32 v66, v183, v66
	ds_write2st64_b32 v64, v65, v66 offset0:16 offset1:17
	v_mul_f32_e32 v65, v34, v92
	v_mul_f32_e32 v66, v35, v93
	v_mul_f32_e32 v65, v183, v65
	v_mul_f32_e32 v66, v183, v66
	ds_write2st64_b32 v64, v65, v66 offset0:18 offset1:19
	v_mul_f32_e32 v65, v36, v89
	v_mul_f32_e32 v66, v37, v91
	v_mul_f32_e32 v65, v183, v65
	v_mul_f32_e32 v66, v183, v66
	ds_write2st64_b32 v64, v65, v66 offset0:20 offset1:21
	v_mul_f32_e32 v65, v38, v80
	v_mul_f32_e32 v66, v39, v81
	v_mul_f32_e32 v65, v183, v65
	v_mul_f32_e32 v66, v183, v66
	ds_write2st64_b32 v64, v65, v66 offset0:22 offset1:23
	v_mul_f32_e32 v65, v40, v87
	v_mul_f32_e32 v66, v41, v88
	v_mul_f32_e32 v65, v183, v65
	v_mul_f32_e32 v66, v183, v66
	ds_write2st64_b32 v64, v65, v66 offset0:24 offset1:25
	v_mul_f32_e32 v65, v42, v85
	v_mul_f32_e32 v66, v43, v86
	v_mul_f32_e32 v65, v183, v65
	v_mul_f32_e32 v66, v183, v66
	ds_write2st64_b32 v64, v65, v66 offset0:26 offset1:27
	v_mul_f32_e32 v65, v44, v83
	v_mul_f32_e32 v66, v45, v84
	v_mul_f32_e32 v65, v183, v65
	v_mul_f32_e32 v66, v183, v66
	ds_write2st64_b32 v64, v65, v66 offset0:28 offset1:29
	v_mul_f32_e32 v65, v46, v82
	v_mul_f32_e32 v66, v47, v79
	v_mul_f32_e32 v65, v183, v65
	v_mul_f32_e32 v66, v183, v66
	ds_write2st64_b32 v64, v65, v66 offset0:30 offset1:31
	v_mul_f32_e32 v65, v16, v94
	v_mul_f32_e32 v66, v17, v96
	v_mul_f32_e32 v65, v183, v65
	v_mul_f32_e32 v66, v183, v66
	ds_write2st64_b32 v64, v65, v66 offset0:32 offset1:33
	v_mul_f32_e32 v65, v18, v92
	v_mul_f32_e32 v66, v19, v93
	v_mul_f32_e32 v65, v183, v65
	v_mul_f32_e32 v66, v183, v66
	ds_write2st64_b32 v64, v65, v66 offset0:34 offset1:35
	v_mul_f32_e32 v65, v20, v89
	v_mul_f32_e32 v66, v21, v91
	v_mul_f32_e32 v65, v183, v65
	v_mul_f32_e32 v66, v183, v66
	ds_write2st64_b32 v64, v65, v66 offset0:36 offset1:37
	v_mul_f32_e32 v65, v22, v80
	v_mul_f32_e32 v66, v23, v81
	v_mul_f32_e32 v65, v183, v65
	v_mul_f32_e32 v66, v183, v66
	ds_write2st64_b32 v64, v65, v66 offset0:38 offset1:39
	v_mul_f32_e32 v65, v24, v87
	v_mul_f32_e32 v66, v25, v88
	v_mul_f32_e32 v65, v183, v65
	v_mul_f32_e32 v66, v183, v66
	ds_write2st64_b32 v64, v65, v66 offset0:40 offset1:41
	v_mul_f32_e32 v65, v26, v85
	v_mul_f32_e32 v66, v27, v86
	v_mul_f32_e32 v65, v183, v65
	v_mul_f32_e32 v66, v183, v66
	ds_write2st64_b32 v64, v65, v66 offset0:42 offset1:43
	v_mul_f32_e32 v65, v28, v83
	v_mul_f32_e32 v66, v29, v84
	v_mul_f32_e32 v65, v183, v65
	v_mul_f32_e32 v66, v183, v66
	ds_write2st64_b32 v64, v65, v66 offset0:44 offset1:45
	v_mul_f32_e32 v65, v30, v82
	v_mul_f32_e32 v66, v31, v79
	v_mul_f32_e32 v65, v183, v65
	v_mul_f32_e32 v66, v183, v66
	ds_write2st64_b32 v64, v65, v66 offset0:46 offset1:47
	v_mul_f32_e32 v65, v0, v94
	v_mul_f32_e32 v66, v1, v96
	v_mul_f32_e32 v65, v183, v65
	v_mul_f32_e32 v66, v183, v66
	ds_write2st64_b32 v64, v65, v66 offset0:48 offset1:49
	v_mul_f32_e32 v65, v2, v92
	v_mul_f32_e32 v66, v3, v93
	v_mul_f32_e32 v65, v183, v65
	v_mul_f32_e32 v66, v183, v66
	ds_write2st64_b32 v64, v65, v66 offset0:50 offset1:51
	v_mul_f32_e32 v65, v4, v89
	v_mul_f32_e32 v66, v5, v91
	v_mul_f32_e32 v65, v183, v65
	v_mul_f32_e32 v66, v183, v66
	ds_write2st64_b32 v64, v65, v66 offset0:52 offset1:53
	v_mul_f32_e32 v65, v6, v80
	v_mul_f32_e32 v66, v7, v81
	v_mul_f32_e32 v65, v183, v65
	v_mul_f32_e32 v66, v183, v66
	ds_write2st64_b32 v64, v65, v66 offset0:54 offset1:55
	v_mul_f32_e32 v65, v8, v87
	v_mul_f32_e32 v66, v9, v88
	v_mul_f32_e32 v65, v183, v65
	v_mul_f32_e32 v66, v183, v66
	ds_write2st64_b32 v64, v65, v66 offset0:56 offset1:57
	v_mul_f32_e32 v65, v10, v85
	v_mul_f32_e32 v66, v11, v86
	v_mul_f32_e32 v65, v183, v65
	v_mul_f32_e32 v66, v183, v66
	ds_write2st64_b32 v64, v65, v66 offset0:58 offset1:59
	v_mul_f32_e32 v65, v12, v83
	v_mul_f32_e32 v66, v13, v84
	v_mul_f32_e32 v65, v183, v65
	v_mul_f32_e32 v66, v183, v66
	ds_write2st64_b32 v64, v65, v66 offset0:60 offset1:61
	v_mul_f32_e32 v65, v14, v82
	v_mul_f32_e32 v66, v15, v79
	v_mul_f32_e32 v65, v183, v65
	v_mul_f32_e32 v66, v183, v66
	ds_write2st64_b32 v64, v65, v66 offset0:62 offset1:63
